# MLP-in GEMM epilogue (P4/P12): the seven later row sum-of-squares loads issued behind the first, per-slice vmcnt(0) waits (which sat out the previous slice's stores) removed
# speedup vs baseline: 1.0026x; 1.0026x over previous
.LBB0_465:
	v_lshl_add_u32 v150, s0, 8, v1
	v_ashrrev_i32_e32 v151, 31, v150
	v_lshl_add_u64 v[148:149], v[150:151], 2, s[72:73]
	global_load_dword v152, v[148:149], off
	global_load_dword v228, v[148:149], off offset:64
	global_load_dword v229, v[148:149], off offset:128
	global_load_dword v230, v[148:149], off offset:192
	global_load_dword v231, v[148:149], off offset:512
	global_load_dword v232, v[148:149], off offset:576
	global_load_dword v233, v[148:149], off offset:640
	global_load_dword v234, v[148:149], off offset:704
	v_lshlrev_b64 v[160:161], 13, v[150:151]
	v_lshl_or_b32 v146, s1, 8, v155
	v_ashrrev_i32_e32 v147, 31, v146
	s_waitcnt vmcnt(0)
	v_fmamk_f32 v151, v152, 0x3a800000, v159
	v_rsq_f32_e32 v162, v151
	v_lshlrev_b64 v[152:153], 1, v[146:147]
	v_lshl_add_u64 v[146:147], s[38:39], 0, v[160:161]
	v_lshl_add_u64 v[146:147], v[146:147], 0, v[152:153]
	v_pk_mul_f32 v[128:129], v[128:129], v[162:163] op_sel_hi:[1,0]
	v_pk_mul_f32 v[126:127], v[126:127], v[162:163] op_sel_hi:[1,0]
	v_pk_mul_f32 v[124:125], v[124:125], v[162:163] op_sel_hi:[1,0]
	v_pk_mul_f32 v[122:123], v[122:123], v[162:163] op_sel_hi:[1,0]
	v_pk_mul_f32 v[120:121], v[120:121], v[162:163] op_sel_hi:[1,0]
	v_pk_mul_f32 v[118:119], v[118:119], v[162:163] op_sel_hi:[1,0]
	v_pk_mul_f32 v[116:117], v[116:117], v[162:163] op_sel_hi:[1,0]
	v_pk_mul_f32 v[114:115], v[114:115], v[162:163] op_sel_hi:[1,0]
	v_max_f32_e32 v126, 0, v126
	v_max_f32_e32 v122, 0, v122
	v_max_f32_e32 v127, 0, v127
	v_max_f32_e32 v123, 0, v123
	v_max_f32_e32 v128, 0, v128
	v_max_f32_e32 v124, 0, v124
	v_max_f32_e32 v129, 0, v129
	v_max_f32_e32 v125, 0, v125
	v_max_f32_e32 v118, 0, v118
	v_max_f32_e32 v114, 0, v114
	v_max_f32_e32 v119, 0, v119
	v_max_f32_e32 v115, 0, v115
	v_max_f32_e32 v120, 0, v120
	v_max_f32_e32 v116, 0, v116
	v_max_f32_e32 v121, 0, v121
	v_max_f32_e32 v117, 0, v117
	v_pk_mul_f32 v[126:127], v[126:127], v[126:127]
	v_pk_mul_f32 v[122:123], v[122:123], v[122:123]
	v_pk_mul_f32 v[128:129], v[128:129], v[128:129]
	v_pk_mul_f32 v[124:125], v[124:125], v[124:125]
	v_pk_mul_f32 v[118:119], v[118:119], v[118:119]
	v_pk_mul_f32 v[160:161], v[114:115], v[114:115]
	v_pk_mul_f32 v[120:121], v[120:121], v[120:121]
	v_pk_mul_f32 v[162:163], v[116:117], v[116:117]
	v_cvt_pk_bf16_f32 v114, v126, v127
	v_cvt_pk_bf16_f32 v115, v128, v129
	v_cvt_pk_bf16_f32 v116, v122, v123
	v_cvt_pk_bf16_f32 v117, v124, v125
	v_cvt_pk_bf16_f32 v118, v118, v119
	v_cvt_pk_bf16_f32 v119, v120, v121
	v_cvt_pk_bf16_f32 v120, v160, v161
	v_cvt_pk_bf16_f32 v121, v162, v163
	global_store_dwordx4 v[146:147], v[114:117], off
	global_store_dwordx4 v[146:147], v[118:121], off offset:256
	s_nop 1
	v_mov_b32_e32 v116, v228
	v_or_b32_e32 v114, 16, v150
	v_ashrrev_i32_e32 v115, 31, v114
	v_lshlrev_b64 v[114:115], 13, v[114:115]
	v_lshl_add_u64 v[114:115], s[38:39], 0, v[114:115]
	v_lshl_add_u64 v[114:115], v[114:115], 0, v[152:153]
	v_fmamk_f32 v116, v116, 0x3a800000, v159
	v_rsq_f32_e32 v116, v116
	s_nop 0
	v_pk_mul_f32 v[112:113], v[112:113], v[116:117] op_sel_hi:[1,0]
	v_pk_mul_f32 v[110:111], v[110:111], v[116:117] op_sel_hi:[1,0]
	v_pk_mul_f32 v[108:109], v[108:109], v[116:117] op_sel_hi:[1,0]
	v_pk_mul_f32 v[106:107], v[106:107], v[116:117] op_sel_hi:[1,0]
	v_pk_mul_f32 v[104:105], v[104:105], v[116:117] op_sel_hi:[1,0]
	v_pk_mul_f32 v[102:103], v[102:103], v[116:117] op_sel_hi:[1,0]
	v_pk_mul_f32 v[100:101], v[100:101], v[116:117] op_sel_hi:[1,0]
	v_pk_mul_f32 v[98:99], v[98:99], v[116:117] op_sel_hi:[1,0]
	v_max_f32_e32 v110, 0, v110
	v_max_f32_e32 v106, 0, v106
	v_max_f32_e32 v111, 0, v111
	v_max_f32_e32 v107, 0, v107
	v_max_f32_e32 v112, 0, v112
	v_max_f32_e32 v108, 0, v108
	v_max_f32_e32 v113, 0, v113
	v_max_f32_e32 v109, 0, v109
	v_max_f32_e32 v102, 0, v102
	v_max_f32_e32 v98, 0, v98
	v_max_f32_e32 v103, 0, v103
	v_max_f32_e32 v99, 0, v99
	v_max_f32_e32 v104, 0, v104
	v_max_f32_e32 v100, 0, v100
	v_max_f32_e32 v105, 0, v105
	v_max_f32_e32 v101, 0, v101
	v_pk_mul_f32 v[110:111], v[110:111], v[110:111]
	v_pk_mul_f32 v[106:107], v[106:107], v[106:107]
	v_pk_mul_f32 v[112:113], v[112:113], v[112:113]
	v_pk_mul_f32 v[108:109], v[108:109], v[108:109]
	v_pk_mul_f32 v[102:103], v[102:103], v[102:103]
	v_pk_mul_f32 v[116:117], v[98:99], v[98:99]
	v_pk_mul_f32 v[104:105], v[104:105], v[104:105]
	v_pk_mul_f32 v[118:119], v[100:101], v[100:101]
	v_cvt_pk_bf16_f32 v98, v110, v111
	v_cvt_pk_bf16_f32 v99, v112, v113
	v_cvt_pk_bf16_f32 v100, v106, v107
	v_cvt_pk_bf16_f32 v101, v108, v109
	v_cvt_pk_bf16_f32 v102, v102, v103
	v_cvt_pk_bf16_f32 v103, v104, v105
	v_cvt_pk_bf16_f32 v104, v116, v117
	v_cvt_pk_bf16_f32 v105, v118, v119
	global_store_dwordx4 v[114:115], v[98:101], off
	global_store_dwordx4 v[114:115], v[102:105], off offset:256
	s_nop 1
	v_mov_b32_e32 v100, v229
	v_or_b32_e32 v98, 32, v150
	v_ashrrev_i32_e32 v99, 31, v98
	v_lshlrev_b64 v[98:99], 13, v[98:99]
	v_lshl_add_u64 v[98:99], s[38:39], 0, v[98:99]
	v_lshl_add_u64 v[98:99], v[98:99], 0, v[152:153]
	v_fmamk_f32 v100, v100, 0x3a800000, v159
	v_rsq_f32_e32 v100, v100
	s_nop 0
	v_pk_mul_f32 v[96:97], v[96:97], v[100:101] op_sel_hi:[1,0]
	v_pk_mul_f32 v[94:95], v[94:95], v[100:101] op_sel_hi:[1,0]
	v_pk_mul_f32 v[92:93], v[92:93], v[100:101] op_sel_hi:[1,0]
	v_pk_mul_f32 v[90:91], v[90:91], v[100:101] op_sel_hi:[1,0]
	v_pk_mul_f32 v[88:89], v[88:89], v[100:101] op_sel_hi:[1,0]
	v_pk_mul_f32 v[86:87], v[86:87], v[100:101] op_sel_hi:[1,0]
	v_pk_mul_f32 v[84:85], v[84:85], v[100:101] op_sel_hi:[1,0]
	v_pk_mul_f32 v[82:83], v[82:83], v[100:101] op_sel_hi:[1,0]
	v_max_f32_e32 v94, 0, v94
	v_max_f32_e32 v90, 0, v90
	v_max_f32_e32 v95, 0, v95
	v_max_f32_e32 v91, 0, v91
	v_max_f32_e32 v96, 0, v96
	v_max_f32_e32 v92, 0, v92
	v_max_f32_e32 v97, 0, v97
	v_max_f32_e32 v93, 0, v93
	v_max_f32_e32 v86, 0, v86
	v_max_f32_e32 v82, 0, v82
	v_max_f32_e32 v87, 0, v87
	v_max_f32_e32 v83, 0, v83
	v_max_f32_e32 v88, 0, v88
	v_max_f32_e32 v84, 0, v84
	v_max_f32_e32 v89, 0, v89
	v_max_f32_e32 v85, 0, v85
	v_pk_mul_f32 v[94:95], v[94:95], v[94:95]
	v_pk_mul_f32 v[90:91], v[90:91], v[90:91]
	v_pk_mul_f32 v[96:97], v[96:97], v[96:97]
	v_pk_mul_f32 v[92:93], v[92:93], v[92:93]
	v_pk_mul_f32 v[86:87], v[86:87], v[86:87]
	v_pk_mul_f32 v[100:101], v[82:83], v[82:83]
	v_pk_mul_f32 v[88:89], v[88:89], v[88:89]
	v_pk_mul_f32 v[102:103], v[84:85], v[84:85]
	v_cvt_pk_bf16_f32 v82, v94, v95
	v_cvt_pk_bf16_f32 v83, v96, v97
	v_cvt_pk_bf16_f32 v84, v90, v91
	v_cvt_pk_bf16_f32 v85, v92, v93
	v_cvt_pk_bf16_f32 v86, v86, v87
	v_cvt_pk_bf16_f32 v87, v88, v89
	v_cvt_pk_bf16_f32 v88, v100, v101
	v_cvt_pk_bf16_f32 v89, v102, v103
	global_store_dwordx4 v[98:99], v[82:85], off
	global_store_dwordx4 v[98:99], v[86:89], off offset:256
	s_nop 1
	v_mov_b32_e32 v84, v230
	v_or_b32_e32 v82, 48, v150
	v_ashrrev_i32_e32 v83, 31, v82
	v_lshlrev_b64 v[82:83], 13, v[82:83]
	v_lshl_add_u64 v[82:83], s[38:39], 0, v[82:83]
	v_lshl_add_u64 v[82:83], v[82:83], 0, v[152:153]
	v_fmamk_f32 v84, v84, 0x3a800000, v159
	v_rsq_f32_e32 v84, v84
	s_nop 0
	v_pk_mul_f32 v[80:81], v[80:81], v[84:85] op_sel_hi:[1,0]
	v_pk_mul_f32 v[78:79], v[78:79], v[84:85] op_sel_hi:[1,0]
	v_pk_mul_f32 v[76:77], v[76:77], v[84:85] op_sel_hi:[1,0]
	v_pk_mul_f32 v[74:75], v[74:75], v[84:85] op_sel_hi:[1,0]
	v_pk_mul_f32 v[72:73], v[72:73], v[84:85] op_sel_hi:[1,0]
	v_pk_mul_f32 v[70:71], v[70:71], v[84:85] op_sel_hi:[1,0]
	v_pk_mul_f32 v[68:69], v[68:69], v[84:85] op_sel_hi:[1,0]
	v_pk_mul_f32 v[66:67], v[66:67], v[84:85] op_sel_hi:[1,0]
	v_max_f32_e32 v78, 0, v78
	v_max_f32_e32 v74, 0, v74
	v_max_f32_e32 v79, 0, v79
	v_max_f32_e32 v75, 0, v75
	v_max_f32_e32 v80, 0, v80
	v_max_f32_e32 v76, 0, v76
	v_max_f32_e32 v81, 0, v81
	v_max_f32_e32 v77, 0, v77
	v_max_f32_e32 v70, 0, v70
	v_max_f32_e32 v66, 0, v66
	v_max_f32_e32 v71, 0, v71
	v_max_f32_e32 v67, 0, v67
	v_max_f32_e32 v72, 0, v72
	v_max_f32_e32 v68, 0, v68
	v_max_f32_e32 v73, 0, v73
	v_max_f32_e32 v69, 0, v69
	v_pk_mul_f32 v[78:79], v[78:79], v[78:79]
	v_pk_mul_f32 v[74:75], v[74:75], v[74:75]
	v_pk_mul_f32 v[80:81], v[80:81], v[80:81]
	v_pk_mul_f32 v[76:77], v[76:77], v[76:77]
	v_pk_mul_f32 v[70:71], v[70:71], v[70:71]
	v_pk_mul_f32 v[84:85], v[66:67], v[66:67]
	v_pk_mul_f32 v[72:73], v[72:73], v[72:73]
	v_pk_mul_f32 v[86:87], v[68:69], v[68:69]
	v_cvt_pk_bf16_f32 v66, v78, v79
	v_cvt_pk_bf16_f32 v67, v80, v81
	v_cvt_pk_bf16_f32 v68, v74, v75
	v_cvt_pk_bf16_f32 v69, v76, v77
	v_cvt_pk_bf16_f32 v70, v70, v71
	v_cvt_pk_bf16_f32 v71, v72, v73
	v_cvt_pk_bf16_f32 v72, v84, v85
	v_cvt_pk_bf16_f32 v73, v86, v87
	global_store_dwordx4 v[82:83], v[66:69], off
	global_store_dwordx4 v[82:83], v[70:73], off offset:256
	s_nop 1
	v_mov_b32_e32 v68, v231
	v_lshl_add_u64 v[66:67], v[146:147], 0, s[14:15]
	v_add_co_u32_e32 v70, vcc, s54, v146
	v_fmamk_f32 v68, v68, 0x3a800000, v159
	v_rsq_f32_e32 v68, v68
	v_addc_co_u32_e32 v71, vcc, 0, v147, vcc
	v_pk_mul_f32 v[64:65], v[64:65], v[68:69] op_sel_hi:[1,0]
	v_pk_mul_f32 v[62:63], v[62:63], v[68:69] op_sel_hi:[1,0]
	v_pk_mul_f32 v[60:61], v[60:61], v[68:69] op_sel_hi:[1,0]
	v_pk_mul_f32 v[58:59], v[58:59], v[68:69] op_sel_hi:[1,0]
	v_pk_mul_f32 v[56:57], v[56:57], v[68:69] op_sel_hi:[1,0]
	v_pk_mul_f32 v[54:55], v[54:55], v[68:69] op_sel_hi:[1,0]
	v_pk_mul_f32 v[52:53], v[52:53], v[68:69] op_sel_hi:[1,0]
	v_pk_mul_f32 v[50:51], v[50:51], v[68:69] op_sel_hi:[1,0]
	v_max_f32_e32 v62, 0, v62
	v_max_f32_e32 v58, 0, v58
	v_max_f32_e32 v63, 0, v63
	v_max_f32_e32 v59, 0, v59
	v_max_f32_e32 v64, 0, v64
	v_max_f32_e32 v60, 0, v60
	v_max_f32_e32 v65, 0, v65
	v_max_f32_e32 v61, 0, v61
	v_max_f32_e32 v54, 0, v54
	v_max_f32_e32 v50, 0, v50
	v_max_f32_e32 v55, 0, v55
	v_max_f32_e32 v51, 0, v51
	v_max_f32_e32 v56, 0, v56
	v_max_f32_e32 v52, 0, v52
	v_max_f32_e32 v57, 0, v57
	v_max_f32_e32 v53, 0, v53
	v_pk_mul_f32 v[62:63], v[62:63], v[62:63]
	v_pk_mul_f32 v[58:59], v[58:59], v[58:59]
	v_pk_mul_f32 v[64:65], v[64:65], v[64:65]
	v_pk_mul_f32 v[60:61], v[60:61], v[60:61]
	v_pk_mul_f32 v[54:55], v[54:55], v[54:55]
	v_pk_mul_f32 v[68:69], v[50:51], v[50:51]
	v_pk_mul_f32 v[56:57], v[56:57], v[56:57]
	v_pk_mul_f32 v[72:73], v[52:53], v[52:53]
	v_cvt_pk_bf16_f32 v50, v62, v63
	v_cvt_pk_bf16_f32 v51, v64, v65
	v_cvt_pk_bf16_f32 v52, v58, v59
	v_cvt_pk_bf16_f32 v53, v60, v61
	v_cvt_pk_bf16_f32 v54, v54, v55
	v_cvt_pk_bf16_f32 v55, v56, v57
	v_cvt_pk_bf16_f32 v56, v68, v69
	v_cvt_pk_bf16_f32 v57, v72, v73
	global_store_dwordx4 v[70:71], v[50:53], off
	global_store_dwordx4 v[66:67], v[54:57], off offset:256
	s_nop 1
	v_mov_b32_e32 v52, v232
	v_lshl_add_u64 v[50:51], v[146:147], 0, s[16:17]
	v_add_co_u32_e32 v54, vcc, s55, v146
	v_fmamk_f32 v52, v52, 0x3a800000, v159
	v_rsq_f32_e32 v52, v52
	v_addc_co_u32_e32 v55, vcc, 0, v147, vcc
	v_pk_mul_f32 v[48:49], v[48:49], v[52:53] op_sel_hi:[1,0]
	v_pk_mul_f32 v[46:47], v[46:47], v[52:53] op_sel_hi:[1,0]
	v_pk_mul_f32 v[44:45], v[44:45], v[52:53] op_sel_hi:[1,0]
	v_pk_mul_f32 v[42:43], v[42:43], v[52:53] op_sel_hi:[1,0]
	v_pk_mul_f32 v[40:41], v[40:41], v[52:53] op_sel_hi:[1,0]
	v_pk_mul_f32 v[38:39], v[38:39], v[52:53] op_sel_hi:[1,0]
	v_pk_mul_f32 v[36:37], v[36:37], v[52:53] op_sel_hi:[1,0]
	v_pk_mul_f32 v[34:35], v[34:35], v[52:53] op_sel_hi:[1,0]
	v_max_f32_e32 v46, 0, v46
	v_max_f32_e32 v42, 0, v42
	v_max_f32_e32 v47, 0, v47
	v_max_f32_e32 v43, 0, v43
	v_max_f32_e32 v48, 0, v48
	v_max_f32_e32 v44, 0, v44
	v_max_f32_e32 v49, 0, v49
	v_max_f32_e32 v45, 0, v45
	v_max_f32_e32 v38, 0, v38
	v_max_f32_e32 v34, 0, v34
	v_max_f32_e32 v39, 0, v39
	v_max_f32_e32 v35, 0, v35
	v_max_f32_e32 v40, 0, v40
	v_max_f32_e32 v36, 0, v36
	v_max_f32_e32 v41, 0, v41
	v_max_f32_e32 v37, 0, v37
	v_pk_mul_f32 v[46:47], v[46:47], v[46:47]
	v_pk_mul_f32 v[42:43], v[42:43], v[42:43]
	v_pk_mul_f32 v[48:49], v[48:49], v[48:49]
	v_pk_mul_f32 v[44:45], v[44:45], v[44:45]
	v_pk_mul_f32 v[38:39], v[38:39], v[38:39]
	v_pk_mul_f32 v[52:53], v[34:35], v[34:35]
	v_pk_mul_f32 v[40:41], v[40:41], v[40:41]
	v_pk_mul_f32 v[56:57], v[36:37], v[36:37]
	v_cvt_pk_bf16_f32 v34, v46, v47
	v_cvt_pk_bf16_f32 v35, v48, v49
	v_cvt_pk_bf16_f32 v36, v42, v43
	v_cvt_pk_bf16_f32 v37, v44, v45
	v_cvt_pk_bf16_f32 v38, v38, v39
	v_cvt_pk_bf16_f32 v39, v40, v41
	v_cvt_pk_bf16_f32 v40, v52, v53
	v_cvt_pk_bf16_f32 v41, v56, v57
	global_store_dwordx4 v[54:55], v[34:37], off
	global_store_dwordx4 v[50:51], v[38:41], off offset:256
	s_nop 1
	v_mov_b32_e32 v36, v233
	v_lshl_add_u64 v[34:35], v[146:147], 0, s[18:19]
	v_add_co_u32_e32 v38, vcc, s56, v146
	v_fmamk_f32 v36, v36, 0x3a800000, v159
	v_rsq_f32_e32 v36, v36
	v_addc_co_u32_e32 v39, vcc, 0, v147, vcc
	s_andn2_b64 vcc, exec, s[2:3]
	v_pk_mul_f32 v[32:33], v[32:33], v[36:37] op_sel_hi:[1,0]
	v_pk_mul_f32 v[30:31], v[30:31], v[36:37] op_sel_hi:[1,0]
	v_pk_mul_f32 v[28:29], v[28:29], v[36:37] op_sel_hi:[1,0]
	v_pk_mul_f32 v[26:27], v[26:27], v[36:37] op_sel_hi:[1,0]
	v_pk_mul_f32 v[24:25], v[24:25], v[36:37] op_sel_hi:[1,0]
	v_pk_mul_f32 v[22:23], v[22:23], v[36:37] op_sel_hi:[1,0]
	v_pk_mul_f32 v[20:21], v[20:21], v[36:37] op_sel_hi:[1,0]
	v_pk_mul_f32 v[18:19], v[18:19], v[36:37] op_sel_hi:[1,0]
	v_max_f32_e32 v30, 0, v30
	v_max_f32_e32 v26, 0, v26
	v_max_f32_e32 v31, 0, v31
	v_max_f32_e32 v27, 0, v27
	v_max_f32_e32 v32, 0, v32
	v_max_f32_e32 v28, 0, v28
	v_max_f32_e32 v33, 0, v33
	v_max_f32_e32 v29, 0, v29
	v_max_f32_e32 v22, 0, v22
	v_max_f32_e32 v18, 0, v18
	v_max_f32_e32 v23, 0, v23
	v_max_f32_e32 v19, 0, v19
	v_max_f32_e32 v24, 0, v24
	v_max_f32_e32 v20, 0, v20
	v_max_f32_e32 v25, 0, v25
	v_max_f32_e32 v21, 0, v21
	v_pk_mul_f32 v[30:31], v[30:31], v[30:31]
	v_pk_mul_f32 v[26:27], v[26:27], v[26:27]
	v_pk_mul_f32 v[32:33], v[32:33], v[32:33]
	v_pk_mul_f32 v[28:29], v[28:29], v[28:29]
	v_pk_mul_f32 v[22:23], v[22:23], v[22:23]
	v_pk_mul_f32 v[36:37], v[18:19], v[18:19]
	v_pk_mul_f32 v[24:25], v[24:25], v[24:25]
	v_pk_mul_f32 v[40:41], v[20:21], v[20:21]
	v_cvt_pk_bf16_f32 v18, v30, v31
	v_cvt_pk_bf16_f32 v19, v32, v33
	v_cvt_pk_bf16_f32 v20, v26, v27
	v_cvt_pk_bf16_f32 v21, v28, v29
	v_cvt_pk_bf16_f32 v22, v22, v23
	v_cvt_pk_bf16_f32 v23, v24, v25
	v_cvt_pk_bf16_f32 v24, v36, v37
	v_cvt_pk_bf16_f32 v25, v40, v41
	global_store_dwordx4 v[38:39], v[18:21], off
	global_store_dwordx4 v[34:35], v[22:25], off offset:256
	s_nop 1
	v_mov_b32_e32 v20, v234
	v_lshl_add_u64 v[18:19], v[146:147], 0, s[20:21]
	v_add_co_u32_e64 v22, s[0:1], s57, v146
	v_fmamk_f32 v20, v20, 0x3a800000, v159
	v_rsq_f32_e32 v20, v20
	v_addc_co_u32_e64 v23, s[0:1], 0, v147, s[0:1]
	s_mov_b64 s[0:1], -1
	v_pk_mul_f32 v[16:17], v[16:17], v[20:21] op_sel_hi:[1,0]
	v_pk_mul_f32 v[14:15], v[14:15], v[20:21] op_sel_hi:[1,0]
	v_pk_mul_f32 v[12:13], v[12:13], v[20:21] op_sel_hi:[1,0]
	v_pk_mul_f32 v[10:11], v[10:11], v[20:21] op_sel_hi:[1,0]
	v_pk_mul_f32 v[8:9], v[8:9], v[20:21] op_sel_hi:[1,0]
	v_pk_mul_f32 v[6:7], v[6:7], v[20:21] op_sel_hi:[1,0]
	v_pk_mul_f32 v[4:5], v[4:5], v[20:21] op_sel_hi:[1,0]
	v_pk_mul_f32 v[2:3], v[2:3], v[20:21] op_sel_hi:[1,0]
	v_max_f32_e32 v14, 0, v14
	v_max_f32_e32 v10, 0, v10
	v_max_f32_e32 v15, 0, v15
	v_max_f32_e32 v11, 0, v11
	v_max_f32_e32 v16, 0, v16
	v_max_f32_e32 v12, 0, v12
	v_max_f32_e32 v17, 0, v17
	v_max_f32_e32 v13, 0, v13
	v_max_f32_e32 v6, 0, v6
	v_max_f32_e32 v2, 0, v2
	v_max_f32_e32 v7, 0, v7
	v_max_f32_e32 v3, 0, v3
	v_max_f32_e32 v8, 0, v8
	v_max_f32_e32 v4, 0, v4
	v_max_f32_e32 v9, 0, v9
	v_max_f32_e32 v5, 0, v5
	v_pk_mul_f32 v[14:15], v[14:15], v[14:15]
	v_pk_mul_f32 v[10:11], v[10:11], v[10:11]
	v_pk_mul_f32 v[16:17], v[16:17], v[16:17]
	v_pk_mul_f32 v[12:13], v[12:13], v[12:13]
	v_pk_mul_f32 v[6:7], v[6:7], v[6:7]
	v_pk_mul_f32 v[20:21], v[2:3], v[2:3]
	v_pk_mul_f32 v[8:9], v[8:9], v[8:9]
	v_pk_mul_f32 v[24:25], v[4:5], v[4:5]
	v_cvt_pk_bf16_f32 v2, v14, v15
	v_cvt_pk_bf16_f32 v3, v16, v17
	v_cvt_pk_bf16_f32 v4, v10, v11
	v_cvt_pk_bf16_f32 v5, v12, v13
	v_cvt_pk_bf16_f32 v6, v6, v7
	v_cvt_pk_bf16_f32 v7, v8, v9
	v_cvt_pk_bf16_f32 v8, v20, v21
	v_cvt_pk_bf16_f32 v9, v24, v25
	global_store_dwordx4 v[22:23], v[2:5], off
	global_store_dwordx4 v[18:19], v[6:9], off offset:256
	s_cbranch_vccnz .LBB0_454
	s_andn2_b64 vcc, exec, s[6:7]
	s_cbranch_vccnz .LBB0_453
	s_barrier
	s_branch .LBB0_453

.LBB0_1667:
	v_lshl_add_u32 v150, s0, 8, v1
	v_ashrrev_i32_e32 v151, 31, v150
	v_lshl_add_u64 v[146:147], v[150:151], 2, s[6:7]
	global_load_dword v164, v[146:147], off
	global_load_dword v228, v[146:147], off offset:64
	global_load_dword v229, v[146:147], off offset:128
	global_load_dword v230, v[146:147], off offset:192
	global_load_dword v231, v[146:147], off offset:512
	global_load_dword v232, v[146:147], off offset:576
	global_load_dword v233, v[146:147], off offset:640
	global_load_dword v234, v[146:147], off offset:704
	v_lshl_or_b32 v148, s1, 8, v155
	v_ashrrev_i32_e32 v149, 31, v148
	v_lshlrev_b64 v[152:153], 1, v[148:149]
	v_lshlrev_b64 v[162:163], 13, v[150:151]
	v_or_b32_e32 v160, 16, v150
	v_ashrrev_i32_e32 v161, 31, v160
	s_waitcnt vmcnt(0)
	v_fmamk_f32 v148, v164, 0x3a800000, v159
	v_rsq_f32_e32 v164, v148
	v_lshl_add_u64 v[148:149], s[38:39], 0, v[162:163]
	v_lshl_add_u64 v[148:149], v[148:149], 0, v[152:153]
	v_lshl_add_u64 v[162:163], v[160:161], 2, s[6:7]
	v_pk_mul_f32 v[128:129], v[128:129], v[164:165] op_sel_hi:[1,0]
	v_pk_mul_f32 v[126:127], v[126:127], v[164:165] op_sel_hi:[1,0]
	v_pk_mul_f32 v[124:125], v[124:125], v[164:165] op_sel_hi:[1,0]
	v_pk_mul_f32 v[122:123], v[122:123], v[164:165] op_sel_hi:[1,0]
	v_pk_mul_f32 v[120:121], v[120:121], v[164:165] op_sel_hi:[1,0]
	v_pk_mul_f32 v[118:119], v[118:119], v[164:165] op_sel_hi:[1,0]
	v_pk_mul_f32 v[116:117], v[116:117], v[164:165] op_sel_hi:[1,0]
	v_pk_mul_f32 v[114:115], v[114:115], v[164:165] op_sel_hi:[1,0]
	v_max_f32_e32 v126, 0, v126
	v_max_f32_e32 v122, 0, v122
	v_max_f32_e32 v127, 0, v127
	v_max_f32_e32 v123, 0, v123
	v_max_f32_e32 v128, 0, v128
	v_max_f32_e32 v124, 0, v124
	v_max_f32_e32 v129, 0, v129
	v_max_f32_e32 v125, 0, v125
	v_max_f32_e32 v118, 0, v118
	v_max_f32_e32 v114, 0, v114
	v_max_f32_e32 v119, 0, v119
	v_max_f32_e32 v115, 0, v115
	v_max_f32_e32 v120, 0, v120
	v_max_f32_e32 v116, 0, v116
	v_max_f32_e32 v121, 0, v121
	v_max_f32_e32 v117, 0, v117
	v_pk_mul_f32 v[126:127], v[126:127], v[126:127]
	v_pk_mul_f32 v[122:123], v[122:123], v[122:123]
	v_pk_mul_f32 v[128:129], v[128:129], v[128:129]
	v_pk_mul_f32 v[124:125], v[124:125], v[124:125]
	v_pk_mul_f32 v[118:119], v[118:119], v[118:119]
	v_pk_mul_f32 v[164:165], v[114:115], v[114:115]
	v_pk_mul_f32 v[120:121], v[120:121], v[120:121]
	v_pk_mul_f32 v[166:167], v[116:117], v[116:117]
	v_cvt_pk_bf16_f32 v114, v126, v127
	v_cvt_pk_bf16_f32 v115, v128, v129
	v_cvt_pk_bf16_f32 v116, v122, v123
	v_cvt_pk_bf16_f32 v117, v124, v125
	v_cvt_pk_bf16_f32 v118, v118, v119
	v_cvt_pk_bf16_f32 v119, v120, v121
	v_cvt_pk_bf16_f32 v120, v164, v165
	v_cvt_pk_bf16_f32 v121, v166, v167
	global_store_dwordx4 v[148:149], v[114:117], off
	global_store_dwordx4 v[148:149], v[118:121], off offset:256
	s_nop 1
	v_mov_b32_e32 v118, v228
	v_lshlrev_b64 v[116:117], 13, v[160:161]
	v_or_b32_e32 v114, 32, v150
	v_lshl_add_u64 v[116:117], s[38:39], 0, v[116:117]
	v_ashrrev_i32_e32 v115, 31, v114
	v_lshl_add_u64 v[116:117], v[116:117], 0, v[152:153]
	v_lshl_add_u64 v[120:121], v[114:115], 2, s[6:7]
	v_fmamk_f32 v118, v118, 0x3a800000, v159
	v_rsq_f32_e32 v118, v118
	s_nop 0
	v_pk_mul_f32 v[112:113], v[112:113], v[118:119] op_sel_hi:[1,0]
	v_pk_mul_f32 v[110:111], v[110:111], v[118:119] op_sel_hi:[1,0]
	v_pk_mul_f32 v[108:109], v[108:109], v[118:119] op_sel_hi:[1,0]
	v_pk_mul_f32 v[106:107], v[106:107], v[118:119] op_sel_hi:[1,0]
	v_pk_mul_f32 v[104:105], v[104:105], v[118:119] op_sel_hi:[1,0]
	v_pk_mul_f32 v[102:103], v[102:103], v[118:119] op_sel_hi:[1,0]
	v_pk_mul_f32 v[100:101], v[100:101], v[118:119] op_sel_hi:[1,0]
	v_pk_mul_f32 v[98:99], v[98:99], v[118:119] op_sel_hi:[1,0]
	v_max_f32_e32 v110, 0, v110
	v_max_f32_e32 v106, 0, v106
	v_max_f32_e32 v111, 0, v111
	v_max_f32_e32 v107, 0, v107
	v_max_f32_e32 v112, 0, v112
	v_max_f32_e32 v108, 0, v108
	v_max_f32_e32 v113, 0, v113
	v_max_f32_e32 v109, 0, v109
	v_max_f32_e32 v102, 0, v102
	v_max_f32_e32 v98, 0, v98
	v_max_f32_e32 v103, 0, v103
	v_max_f32_e32 v99, 0, v99
	v_max_f32_e32 v104, 0, v104
	v_max_f32_e32 v100, 0, v100
	v_max_f32_e32 v105, 0, v105
	v_max_f32_e32 v101, 0, v101
	v_pk_mul_f32 v[110:111], v[110:111], v[110:111]
	v_pk_mul_f32 v[106:107], v[106:107], v[106:107]
	v_pk_mul_f32 v[112:113], v[112:113], v[112:113]
	v_pk_mul_f32 v[108:109], v[108:109], v[108:109]
	v_pk_mul_f32 v[102:103], v[102:103], v[102:103]
	v_pk_mul_f32 v[118:119], v[98:99], v[98:99]
	v_pk_mul_f32 v[104:105], v[104:105], v[104:105]
	v_pk_mul_f32 v[122:123], v[100:101], v[100:101]
	v_cvt_pk_bf16_f32 v98, v110, v111
	v_cvt_pk_bf16_f32 v99, v112, v113
	v_cvt_pk_bf16_f32 v100, v106, v107
	v_cvt_pk_bf16_f32 v101, v108, v109
	v_cvt_pk_bf16_f32 v102, v102, v103
	v_cvt_pk_bf16_f32 v103, v104, v105
	v_cvt_pk_bf16_f32 v104, v118, v119
	v_cvt_pk_bf16_f32 v105, v122, v123
	global_store_dwordx4 v[116:117], v[98:101], off
	global_store_dwordx4 v[116:117], v[102:105], off offset:256
	s_nop 1
	v_mov_b32_e32 v102, v229
	v_lshlrev_b64 v[100:101], 13, v[114:115]
	v_or_b32_e32 v98, 48, v150
	v_lshl_add_u64 v[100:101], s[38:39], 0, v[100:101]
	v_ashrrev_i32_e32 v99, 31, v98
	v_lshl_add_u64 v[100:101], v[100:101], 0, v[152:153]
	v_lshl_add_u64 v[104:105], v[98:99], 2, s[6:7]
	v_fmamk_f32 v102, v102, 0x3a800000, v159
	v_rsq_f32_e32 v102, v102
	s_nop 0
	v_pk_mul_f32 v[96:97], v[96:97], v[102:103] op_sel_hi:[1,0]
	v_pk_mul_f32 v[94:95], v[94:95], v[102:103] op_sel_hi:[1,0]
	v_pk_mul_f32 v[92:93], v[92:93], v[102:103] op_sel_hi:[1,0]
	v_pk_mul_f32 v[90:91], v[90:91], v[102:103] op_sel_hi:[1,0]
	v_pk_mul_f32 v[88:89], v[88:89], v[102:103] op_sel_hi:[1,0]
	v_pk_mul_f32 v[86:87], v[86:87], v[102:103] op_sel_hi:[1,0]
	v_pk_mul_f32 v[84:85], v[84:85], v[102:103] op_sel_hi:[1,0]
	v_pk_mul_f32 v[82:83], v[82:83], v[102:103] op_sel_hi:[1,0]
	v_max_f32_e32 v94, 0, v94
	v_max_f32_e32 v90, 0, v90
	v_max_f32_e32 v95, 0, v95
	v_max_f32_e32 v91, 0, v91
	v_max_f32_e32 v96, 0, v96
	v_max_f32_e32 v92, 0, v92
	v_max_f32_e32 v97, 0, v97
	v_max_f32_e32 v93, 0, v93
	v_max_f32_e32 v86, 0, v86
	v_max_f32_e32 v82, 0, v82
	v_max_f32_e32 v87, 0, v87
	v_max_f32_e32 v83, 0, v83
	v_max_f32_e32 v88, 0, v88
	v_max_f32_e32 v84, 0, v84
	v_max_f32_e32 v89, 0, v89
	v_max_f32_e32 v85, 0, v85
	v_pk_mul_f32 v[94:95], v[94:95], v[94:95]
	v_pk_mul_f32 v[90:91], v[90:91], v[90:91]
	v_pk_mul_f32 v[96:97], v[96:97], v[96:97]
	v_pk_mul_f32 v[92:93], v[92:93], v[92:93]
	v_pk_mul_f32 v[86:87], v[86:87], v[86:87]
	v_pk_mul_f32 v[102:103], v[82:83], v[82:83]
	v_pk_mul_f32 v[88:89], v[88:89], v[88:89]
	v_pk_mul_f32 v[106:107], v[84:85], v[84:85]
	v_cvt_pk_bf16_f32 v82, v94, v95
	v_cvt_pk_bf16_f32 v83, v96, v97
	v_cvt_pk_bf16_f32 v84, v90, v91
	v_cvt_pk_bf16_f32 v85, v92, v93
	v_cvt_pk_bf16_f32 v86, v86, v87
	v_cvt_pk_bf16_f32 v87, v88, v89
	v_cvt_pk_bf16_f32 v88, v102, v103
	v_cvt_pk_bf16_f32 v89, v106, v107
	global_store_dwordx4 v[100:101], v[82:85], off
	global_store_dwordx4 v[100:101], v[86:89], off offset:256
	s_nop 1
	v_mov_b32_e32 v82, v230
	v_lshlrev_b64 v[84:85], 13, v[98:99]
	v_lshl_add_u64 v[84:85], s[38:39], 0, v[84:85]
	v_lshl_add_u64 v[84:85], v[84:85], 0, v[152:153]
	v_fmamk_f32 v82, v82, 0x3a800000, v159
	v_rsq_f32_e32 v82, v82
	s_nop 0
	v_pk_mul_f32 v[80:81], v[80:81], v[82:83] op_sel_hi:[1,0]
	v_pk_mul_f32 v[78:79], v[78:79], v[82:83] op_sel_hi:[1,0]
	v_pk_mul_f32 v[76:77], v[76:77], v[82:83] op_sel_hi:[1,0]
	v_pk_mul_f32 v[74:75], v[74:75], v[82:83] op_sel_hi:[1,0]
	v_pk_mul_f32 v[72:73], v[72:73], v[82:83] op_sel_hi:[1,0]
	v_pk_mul_f32 v[70:71], v[70:71], v[82:83] op_sel_hi:[1,0]
	v_pk_mul_f32 v[68:69], v[68:69], v[82:83] op_sel_hi:[1,0]
	v_pk_mul_f32 v[66:67], v[66:67], v[82:83] op_sel_hi:[1,0]
	v_max_f32_e32 v78, 0, v78
	v_max_f32_e32 v74, 0, v74
	v_max_f32_e32 v79, 0, v79
	v_max_f32_e32 v75, 0, v75
	v_max_f32_e32 v80, 0, v80
	v_max_f32_e32 v76, 0, v76
	v_max_f32_e32 v81, 0, v81
	v_max_f32_e32 v77, 0, v77
	v_max_f32_e32 v70, 0, v70
	v_max_f32_e32 v66, 0, v66
	v_max_f32_e32 v71, 0, v71
	v_max_f32_e32 v67, 0, v67
	v_max_f32_e32 v72, 0, v72
	v_max_f32_e32 v68, 0, v68
	v_max_f32_e32 v73, 0, v73
	v_max_f32_e32 v69, 0, v69
	v_pk_mul_f32 v[78:79], v[78:79], v[78:79]
	v_pk_mul_f32 v[74:75], v[74:75], v[74:75]
	v_pk_mul_f32 v[80:81], v[80:81], v[80:81]
	v_pk_mul_f32 v[76:77], v[76:77], v[76:77]
	v_pk_mul_f32 v[70:71], v[70:71], v[70:71]
	v_pk_mul_f32 v[82:83], v[66:67], v[66:67]
	v_pk_mul_f32 v[72:73], v[72:73], v[72:73]
	v_pk_mul_f32 v[86:87], v[68:69], v[68:69]
	v_cvt_pk_bf16_f32 v66, v78, v79
	v_cvt_pk_bf16_f32 v67, v80, v81
	v_cvt_pk_bf16_f32 v68, v74, v75
	v_cvt_pk_bf16_f32 v69, v76, v77
	v_cvt_pk_bf16_f32 v70, v70, v71
	v_cvt_pk_bf16_f32 v71, v72, v73
	v_cvt_pk_bf16_f32 v72, v82, v83
	v_cvt_pk_bf16_f32 v73, v86, v87
	global_store_dwordx4 v[84:85], v[66:69], off
	global_store_dwordx4 v[84:85], v[70:73], off offset:256
	s_nop 1
	v_mov_b32_e32 v68, v231
	v_lshl_add_u64 v[66:67], v[148:149], 0, s[16:17]
	v_add_co_u32_e32 v70, vcc, s54, v148
	v_fmamk_f32 v68, v68, 0x3a800000, v159
	v_rsq_f32_e32 v68, v68
	v_addc_co_u32_e32 v71, vcc, 0, v149, vcc
	v_pk_mul_f32 v[64:65], v[64:65], v[68:69] op_sel_hi:[1,0]
	v_pk_mul_f32 v[62:63], v[62:63], v[68:69] op_sel_hi:[1,0]
	v_pk_mul_f32 v[60:61], v[60:61], v[68:69] op_sel_hi:[1,0]
	v_pk_mul_f32 v[58:59], v[58:59], v[68:69] op_sel_hi:[1,0]
	v_pk_mul_f32 v[56:57], v[56:57], v[68:69] op_sel_hi:[1,0]
	v_pk_mul_f32 v[54:55], v[54:55], v[68:69] op_sel_hi:[1,0]
	v_pk_mul_f32 v[52:53], v[52:53], v[68:69] op_sel_hi:[1,0]
	v_pk_mul_f32 v[50:51], v[50:51], v[68:69] op_sel_hi:[1,0]
	v_max_f32_e32 v62, 0, v62
	v_max_f32_e32 v58, 0, v58
	v_max_f32_e32 v63, 0, v63
	v_max_f32_e32 v59, 0, v59
	v_max_f32_e32 v64, 0, v64
	v_max_f32_e32 v60, 0, v60
	v_max_f32_e32 v65, 0, v65
	v_max_f32_e32 v61, 0, v61
	v_max_f32_e32 v54, 0, v54
	v_max_f32_e32 v50, 0, v50
	v_max_f32_e32 v55, 0, v55
	v_max_f32_e32 v51, 0, v51
	v_max_f32_e32 v56, 0, v56
	v_max_f32_e32 v52, 0, v52
	v_max_f32_e32 v57, 0, v57
	v_max_f32_e32 v53, 0, v53
	v_pk_mul_f32 v[62:63], v[62:63], v[62:63]
	v_pk_mul_f32 v[58:59], v[58:59], v[58:59]
	v_pk_mul_f32 v[64:65], v[64:65], v[64:65]
	v_pk_mul_f32 v[60:61], v[60:61], v[60:61]
	v_pk_mul_f32 v[54:55], v[54:55], v[54:55]
	v_pk_mul_f32 v[68:69], v[50:51], v[50:51]
	v_pk_mul_f32 v[56:57], v[56:57], v[56:57]
	v_pk_mul_f32 v[72:73], v[52:53], v[52:53]
	v_cvt_pk_bf16_f32 v50, v62, v63
	v_cvt_pk_bf16_f32 v51, v64, v65
	v_cvt_pk_bf16_f32 v52, v58, v59
	v_cvt_pk_bf16_f32 v53, v60, v61
	v_cvt_pk_bf16_f32 v54, v54, v55
	v_cvt_pk_bf16_f32 v55, v56, v57
	v_cvt_pk_bf16_f32 v56, v68, v69
	v_cvt_pk_bf16_f32 v57, v72, v73
	global_store_dwordx4 v[70:71], v[50:53], off
	global_store_dwordx4 v[66:67], v[54:57], off offset:256
	s_nop 1
	v_mov_b32_e32 v52, v232
	v_lshl_add_u64 v[50:51], v[148:149], 0, s[18:19]
	v_add_co_u32_e32 v54, vcc, s55, v148
	v_fmamk_f32 v52, v52, 0x3a800000, v159
	v_rsq_f32_e32 v52, v52
	v_addc_co_u32_e32 v55, vcc, 0, v149, vcc
	v_pk_mul_f32 v[48:49], v[48:49], v[52:53] op_sel_hi:[1,0]
	v_pk_mul_f32 v[46:47], v[46:47], v[52:53] op_sel_hi:[1,0]
	v_pk_mul_f32 v[44:45], v[44:45], v[52:53] op_sel_hi:[1,0]
	v_pk_mul_f32 v[42:43], v[42:43], v[52:53] op_sel_hi:[1,0]
	v_pk_mul_f32 v[40:41], v[40:41], v[52:53] op_sel_hi:[1,0]
	v_pk_mul_f32 v[38:39], v[38:39], v[52:53] op_sel_hi:[1,0]
	v_pk_mul_f32 v[36:37], v[36:37], v[52:53] op_sel_hi:[1,0]
	v_pk_mul_f32 v[34:35], v[34:35], v[52:53] op_sel_hi:[1,0]
	v_max_f32_e32 v46, 0, v46
	v_max_f32_e32 v42, 0, v42
	v_max_f32_e32 v47, 0, v47
	v_max_f32_e32 v43, 0, v43
	v_max_f32_e32 v48, 0, v48
	v_max_f32_e32 v44, 0, v44
	v_max_f32_e32 v49, 0, v49
	v_max_f32_e32 v45, 0, v45
	v_max_f32_e32 v38, 0, v38
	v_max_f32_e32 v34, 0, v34
	v_max_f32_e32 v39, 0, v39
	v_max_f32_e32 v35, 0, v35
	v_max_f32_e32 v40, 0, v40
	v_max_f32_e32 v36, 0, v36
	v_max_f32_e32 v41, 0, v41
	v_max_f32_e32 v37, 0, v37
	v_pk_mul_f32 v[46:47], v[46:47], v[46:47]
	v_pk_mul_f32 v[42:43], v[42:43], v[42:43]
	v_pk_mul_f32 v[48:49], v[48:49], v[48:49]
	v_pk_mul_f32 v[44:45], v[44:45], v[44:45]
	v_pk_mul_f32 v[38:39], v[38:39], v[38:39]
	v_pk_mul_f32 v[52:53], v[34:35], v[34:35]
	v_pk_mul_f32 v[40:41], v[40:41], v[40:41]
	v_pk_mul_f32 v[56:57], v[36:37], v[36:37]
	v_cvt_pk_bf16_f32 v34, v46, v47
	v_cvt_pk_bf16_f32 v35, v48, v49
	v_cvt_pk_bf16_f32 v36, v42, v43
	v_cvt_pk_bf16_f32 v37, v44, v45
	v_cvt_pk_bf16_f32 v38, v38, v39
	v_cvt_pk_bf16_f32 v39, v40, v41
	v_cvt_pk_bf16_f32 v40, v52, v53
	v_cvt_pk_bf16_f32 v41, v56, v57
	global_store_dwordx4 v[54:55], v[34:37], off
	global_store_dwordx4 v[50:51], v[38:41], off offset:256
	s_nop 1
	v_mov_b32_e32 v36, v233
	v_lshl_add_u64 v[34:35], v[148:149], 0, s[20:21]
	v_add_co_u32_e32 v38, vcc, s56, v148
	v_fmamk_f32 v36, v36, 0x3a800000, v159
	v_rsq_f32_e32 v36, v36
	v_addc_co_u32_e32 v39, vcc, 0, v149, vcc
	s_andn2_b64 vcc, exec, s[2:3]
	v_pk_mul_f32 v[32:33], v[32:33], v[36:37] op_sel_hi:[1,0]
	v_pk_mul_f32 v[30:31], v[30:31], v[36:37] op_sel_hi:[1,0]
	v_pk_mul_f32 v[28:29], v[28:29], v[36:37] op_sel_hi:[1,0]
	v_pk_mul_f32 v[26:27], v[26:27], v[36:37] op_sel_hi:[1,0]
	v_pk_mul_f32 v[24:25], v[24:25], v[36:37] op_sel_hi:[1,0]
	v_pk_mul_f32 v[22:23], v[22:23], v[36:37] op_sel_hi:[1,0]
	v_pk_mul_f32 v[20:21], v[20:21], v[36:37] op_sel_hi:[1,0]
	v_pk_mul_f32 v[18:19], v[18:19], v[36:37] op_sel_hi:[1,0]
	v_max_f32_e32 v30, 0, v30
	v_max_f32_e32 v26, 0, v26
	v_max_f32_e32 v31, 0, v31
	v_max_f32_e32 v27, 0, v27
	v_max_f32_e32 v32, 0, v32
	v_max_f32_e32 v28, 0, v28
	v_max_f32_e32 v33, 0, v33
	v_max_f32_e32 v29, 0, v29
	v_max_f32_e32 v22, 0, v22
	v_max_f32_e32 v18, 0, v18
	v_max_f32_e32 v23, 0, v23
	v_max_f32_e32 v19, 0, v19
	v_max_f32_e32 v24, 0, v24
	v_max_f32_e32 v20, 0, v20
	v_max_f32_e32 v25, 0, v25
	v_max_f32_e32 v21, 0, v21
	v_pk_mul_f32 v[30:31], v[30:31], v[30:31]
	v_pk_mul_f32 v[26:27], v[26:27], v[26:27]
	v_pk_mul_f32 v[32:33], v[32:33], v[32:33]
	v_pk_mul_f32 v[28:29], v[28:29], v[28:29]
	v_pk_mul_f32 v[22:23], v[22:23], v[22:23]
	v_pk_mul_f32 v[36:37], v[18:19], v[18:19]
	v_pk_mul_f32 v[24:25], v[24:25], v[24:25]
	v_pk_mul_f32 v[40:41], v[20:21], v[20:21]
	v_cvt_pk_bf16_f32 v18, v30, v31
	v_cvt_pk_bf16_f32 v19, v32, v33
	v_cvt_pk_bf16_f32 v20, v26, v27
	v_cvt_pk_bf16_f32 v21, v28, v29
	v_cvt_pk_bf16_f32 v22, v22, v23
	v_cvt_pk_bf16_f32 v23, v24, v25
	v_cvt_pk_bf16_f32 v24, v36, v37
	v_cvt_pk_bf16_f32 v25, v40, v41
	global_store_dwordx4 v[38:39], v[18:21], off
	global_store_dwordx4 v[34:35], v[22:25], off offset:256
	s_nop 1
	v_mov_b32_e32 v20, v234
	v_lshl_add_u64 v[18:19], v[148:149], 0, s[22:23]
	v_add_co_u32_e64 v22, s[0:1], s57, v148
	v_fmamk_f32 v20, v20, 0x3a800000, v159
	v_rsq_f32_e32 v20, v20
	v_addc_co_u32_e64 v23, s[0:1], 0, v149, s[0:1]
	s_mov_b64 s[0:1], -1
	v_pk_mul_f32 v[16:17], v[16:17], v[20:21] op_sel_hi:[1,0]
	v_pk_mul_f32 v[14:15], v[14:15], v[20:21] op_sel_hi:[1,0]
	v_pk_mul_f32 v[12:13], v[12:13], v[20:21] op_sel_hi:[1,0]
	v_pk_mul_f32 v[10:11], v[10:11], v[20:21] op_sel_hi:[1,0]
	v_pk_mul_f32 v[8:9], v[8:9], v[20:21] op_sel_hi:[1,0]
	v_pk_mul_f32 v[6:7], v[6:7], v[20:21] op_sel_hi:[1,0]
	v_pk_mul_f32 v[4:5], v[4:5], v[20:21] op_sel_hi:[1,0]
	v_pk_mul_f32 v[2:3], v[2:3], v[20:21] op_sel_hi:[1,0]
	v_max_f32_e32 v14, 0, v14
	v_max_f32_e32 v10, 0, v10
	v_max_f32_e32 v15, 0, v15
	v_max_f32_e32 v11, 0, v11
	v_max_f32_e32 v16, 0, v16
	v_max_f32_e32 v12, 0, v12
	v_max_f32_e32 v17, 0, v17
	v_max_f32_e32 v13, 0, v13
	v_max_f32_e32 v6, 0, v6
	v_max_f32_e32 v2, 0, v2
	v_max_f32_e32 v7, 0, v7
	v_max_f32_e32 v3, 0, v3
	v_max_f32_e32 v8, 0, v8
	v_max_f32_e32 v4, 0, v4
	v_max_f32_e32 v9, 0, v9
	v_max_f32_e32 v5, 0, v5
	v_pk_mul_f32 v[14:15], v[14:15], v[14:15]
	v_pk_mul_f32 v[10:11], v[10:11], v[10:11]
	v_pk_mul_f32 v[16:17], v[16:17], v[16:17]
	v_pk_mul_f32 v[12:13], v[12:13], v[12:13]
	v_pk_mul_f32 v[6:7], v[6:7], v[6:7]
	v_pk_mul_f32 v[20:21], v[2:3], v[2:3]
	v_pk_mul_f32 v[8:9], v[8:9], v[8:9]
	v_pk_mul_f32 v[24:25], v[4:5], v[4:5]
	v_cvt_pk_bf16_f32 v2, v14, v15
	v_cvt_pk_bf16_f32 v3, v16, v17
	v_cvt_pk_bf16_f32 v4, v10, v11
	v_cvt_pk_bf16_f32 v5, v12, v13
	v_cvt_pk_bf16_f32 v6, v6, v7
	v_cvt_pk_bf16_f32 v7, v8, v9
	v_cvt_pk_bf16_f32 v8, v20, v21
	v_cvt_pk_bf16_f32 v9, v24, v25
	global_store_dwordx4 v[22:23], v[2:5], off
	global_store_dwordx4 v[18:19], v[6:9], off offset:256
	s_cbranch_vccnz .LBB0_1656
	s_andn2_b64 vcc, exec, s[8:9]
	s_cbranch_vccnz .LBB0_1655
	s_barrier
	s_branch .LBB0_1655
